# LRU pass-0 item constants: 11 loads issued together + hw exp2/log2 softplus (same change as pass 1)
# speedup vs baseline: 1.0283x; 1.0033x over previous
; #define LAS __attribute__((address_space(3)))
; template <int PASS> __device__ __forceinline__ void phase_lru(LAS unsigned char* lds, const bf16_t* Z, const bf16_t* WL, float* LSUM, const float* LCAR, bf16_t* RNN,
;                                                               int S, int tid, int lane, int wave, int G) {
;     ...
;         bf16x8 wf[4][4];
; #pragma unroll
;         for (int q = 0; q < 4; ++q)
; #pragma unroll
;             for (int s = 0; s < 4; ++s) wf[q][s] = *(const bf16x8*)(WL + ((size_t)((n * 4 + q) * 128 + wave * 16 + c)) * 128 + 32 * s + 8 * g4);
;         LAS f32x4* kc = (LAS f32x4*)(lds + LRU_KC + wave * 11264);
; #pragma unroll
;         for (int k = 0; k < 4; ++k) kc[(6 + k) * 64 + lane] = *(const f32x4*)(conv_w + k * LW + ch0);
;         kc[10 * 64 + lane] = *(const f32x4*)(conv_b + ch0);
; #pragma unroll
;         for (int d = 0; d < 2; ++d) { kc[(3 * d + 0) * 64 + lane] = *(const f32x4*)(lba + d * LW + ch0) * (-LOG2E); kc[(3 * d + 1) * 64 + lane] = *(const f32x4*)(lbx + d * LW + ch0) * (-LOG2E);
;             const f32x4 lv = *(const f32x4*)(lam + d * LW + ch0); f32x4 sp;
; #pragma unroll
;             for (int j = 0; j < 4; ++j) sp[j] = -8.0f * LOG2E * log1pf(expf(-lv[j]));
;             kc[(3 * d + 2) * 64 + lane] = sp; }
;     ...
;         u32x4 rawr[3];
;     ...
;         LRU_LOAD_RAW(run * 4)
.LBB0_213:
	s_ashr_i32 s0, s57, 6
	v_lshl_add_u32 v2, s0, 9, v154
	v_ashrrev_i32_e32 v3, 31, v2
	v_lshlrev_b64 v[4:5], 8, v[2:3]
	v_add_u32_e32 v20, 0x80, v2
	v_add_u32_e32 v36, 0x100, v2
	v_add_u32_e32 v2, 0x180, v2
	s_lshl_b32 s58, s0, 7
	v_ashrrev_i32_e32 v21, 31, v20
	v_ashrrev_i32_e32 v37, 31, v36
	v_ashrrev_i32_e32 v3, 31, v2
	v_lshlrev_b64 v[20:21], 8, v[20:21]
	v_lshlrev_b64 v[36:37], 8, v[36:37]
	v_lshlrev_b64 v[2:3], 8, v[2:3]
	v_add_u32_e32 v80, s58, v153
	v_lshl_add_u64 v[16:17], v[100:101], 0, v[4:5]
	v_lshl_add_u64 v[32:33], v[100:101], 0, v[20:21]
	v_lshl_add_u64 v[48:49], v[100:101], 0, v[36:37]
	v_lshl_add_u64 v[2:3], v[100:101], 0, v[2:3]
	v_ashrrev_i32_e32 v81, 31, v80
	global_load_dwordx4 v[4:7], v[16:17], off
	global_load_dwordx4 v[8:11], v[16:17], off offset:64
	global_load_dwordx4 v[12:15], v[16:17], off offset:128
	s_nop 0
	global_load_dwordx4 v[16:19], v[16:17], off offset:192
	s_nop 0
	global_load_dwordx4 v[20:23], v[32:33], off
	global_load_dwordx4 v[24:27], v[32:33], off offset:64
	global_load_dwordx4 v[28:31], v[32:33], off offset:128
	s_nop 0
	global_load_dwordx4 v[32:35], v[32:33], off offset:192
	s_nop 0
	global_load_dwordx4 v[36:39], v[48:49], off
	global_load_dwordx4 v[40:43], v[48:49], off offset:64
	global_load_dwordx4 v[44:47], v[48:49], off offset:128
	s_nop 0
	global_load_dwordx4 v[48:51], v[48:49], off offset:192
	s_nop 0
	global_load_dwordx4 v[52:55], v[2:3], off
	global_load_dwordx4 v[56:59], v[2:3], off offset:64
	global_load_dwordx4 v[60:63], v[2:3], off offset:128
	global_load_dwordx4 v[64:67], v[2:3], off offset:192
	v_lshlrev_b64 v[2:3], 2, v[80:81]
	s_waitcnt vmcnt(0)
	s_ashr_i32 s59, s58, 31
	v_add_u32_e32 v1, 0x1800, v2
	v_add_u32_e32 v3, 0x3000, v2
	v_add_u32_e32 v106, 0x4800, v2
	global_load_dwordx4 v[68:71], v2, s[4:5]
	global_load_dwordx4 v[72:75], v1, s[4:5]
	global_load_dwordx4 v[76:79], v3, s[4:5]
	global_load_dwordx4 v[84:87], v106, s[4:5]
	global_load_dwordx4 v[88:91], v2, s[12:13]
	global_load_dwordx4 v[92:95], v2, s[36:37]
	global_load_dwordx4 v[96:99], v2, s[94:95]
	global_load_dwordx4 v[108:111], v2, s[96:97]
	global_load_dwordx4 v[204:207], v1, s[36:37]
	global_load_dwordx4 v[208:211], v1, s[94:95]
	global_load_dwordx4 v[212:215], v1, s[96:97]
	s_mov_b32 s76, 0xc1000000
	s_waitcnt vmcnt(0)
	ds_write_b128 v155, v[68:71] offset:43008
	ds_write_b128 v155, v[72:75] offset:44032
	ds_write_b128 v155, v[76:79] offset:45056
	ds_write_b128 v155, v[84:87] offset:46080
	ds_write_b128 v155, v[88:91] offset:47104
	v_pk_mul_f32 v[92:93], v[92:93], s[24:25] op_sel_hi:[1,0]
	v_pk_mul_f32 v[94:95], v[94:95], s[24:25] op_sel_hi:[1,0]
	v_pk_mul_f32 v[96:97], v[96:97], s[24:25] op_sel_hi:[1,0]
	v_pk_mul_f32 v[98:99], v[98:99], s[24:25] op_sel_hi:[1,0]
	v_pk_mul_f32 v[204:205], v[204:205], s[24:25] op_sel_hi:[1,0]
	v_pk_mul_f32 v[206:207], v[206:207], s[24:25] op_sel_hi:[1,0]
	v_pk_mul_f32 v[208:209], v[208:209], s[24:25] op_sel_hi:[1,0]
	v_pk_mul_f32 v[210:211], v[210:211], s[24:25] op_sel_hi:[1,0]
	ds_write_b128 v155, v[92:95] offset:36864
	ds_write_b128 v155, v[96:99] offset:37888
	ds_write_b128 v155, v[204:207] offset:39936
	ds_write_b128 v155, v[208:211] offset:40960
	v_mul_f32_e32 v68, s24, v108
	v_mul_f32_e32 v69, s24, v109
	v_mul_f32_e32 v70, s24, v110
	v_mul_f32_e32 v71, s24, v111
	v_mul_f32_e32 v72, s24, v212
	v_mul_f32_e32 v73, s24, v213
	v_mul_f32_e32 v74, s24, v214
	v_mul_f32_e32 v75, s24, v215
	v_exp_f32_e32 v68, v68
	v_exp_f32_e32 v69, v69
	v_exp_f32_e32 v70, v70
	v_exp_f32_e32 v71, v71
	v_exp_f32_e32 v72, v72
	v_exp_f32_e32 v73, v73
	v_exp_f32_e32 v74, v74
	v_exp_f32_e32 v75, v75
	v_add_f32_e32 v76, 1.0, v68
	v_add_f32_e32 v77, 1.0, v69
	v_add_f32_e32 v78, 1.0, v70
	v_add_f32_e32 v79, 1.0, v71
	v_add_f32_e32 v84, 1.0, v72
	v_add_f32_e32 v85, 1.0, v73
	v_add_f32_e32 v86, 1.0, v74
	v_add_f32_e32 v87, 1.0, v75
	v_add_f32_e32 v88, -1.0, v76
	v_add_f32_e32 v89, -1.0, v77
	v_add_f32_e32 v90, -1.0, v78
	v_add_f32_e32 v91, -1.0, v79
	v_add_f32_e32 v92, -1.0, v84
	v_add_f32_e32 v93, -1.0, v85
	v_add_f32_e32 v94, -1.0, v86
	v_add_f32_e32 v95, -1.0, v87
	v_log_f32_e32 v76, v76
	v_log_f32_e32 v77, v77
	v_log_f32_e32 v78, v78
	v_log_f32_e32 v79, v79
	v_log_f32_e32 v84, v84
	v_log_f32_e32 v85, v85
	v_log_f32_e32 v86, v86
	v_log_f32_e32 v87, v87
	v_max_f32_e32 v88, 0x33800000, v88
	v_max_f32_e32 v89, 0x33800000, v89
	v_max_f32_e32 v90, 0x33800000, v90
	v_max_f32_e32 v91, 0x33800000, v91
	v_max_f32_e32 v92, 0x33800000, v92
	v_max_f32_e32 v93, 0x33800000, v93
	v_max_f32_e32 v94, 0x33800000, v94
	v_max_f32_e32 v95, 0x33800000, v95
	v_rcp_f32_e32 v88, v88
	v_rcp_f32_e32 v89, v89
	v_rcp_f32_e32 v90, v90
	v_rcp_f32_e32 v91, v91
	v_rcp_f32_e32 v92, v92
	v_rcp_f32_e32 v93, v93
	v_rcp_f32_e32 v94, v94
	v_rcp_f32_e32 v95, v95
	v_mul_f32_e32 v68, v68, v88
	v_mul_f32_e32 v69, v69, v89
	v_mul_f32_e32 v70, v70, v90
	v_mul_f32_e32 v71, v71, v91
	v_mul_f32_e32 v72, v72, v92
	v_mul_f32_e32 v73, v73, v93
	v_mul_f32_e32 v74, v74, v94
	v_mul_f32_e32 v75, v75, v95
	v_mul_f32_e32 v76, v76, v68
	v_mul_f32_e32 v77, v77, v69
	v_mul_f32_e32 v78, v78, v70
	v_mul_f32_e32 v79, v79, v71
	v_mul_f32_e32 v84, v84, v72
	v_mul_f32_e32 v85, v85, v73
	v_mul_f32_e32 v86, v86, v74
	v_mul_f32_e32 v87, v87, v75
	v_mul_f32_e32 v108, s76, v76
	v_mul_f32_e32 v109, s76, v77
	v_mul_f32_e32 v110, s76, v78
	v_mul_f32_e32 v111, s76, v79
	v_mul_f32_e32 v212, s76, v84
	v_mul_f32_e32 v213, s76, v85
	v_mul_f32_e32 v214, s76, v86
	v_mul_f32_e32 v215, s76, v87
	ds_write_b128 v155, v[108:111] offset:38912
	ds_write_b128 v155, v[212:215] offset:41984
	v_lshlrev_b32_e32 v82, 1, v102
	s_lshl_b32 s0, s57, 8
	s_and_b32 s18, s0, 0x3f00
	s_and_b32 s19, s18, s30
	s_add_i32 s19, s19, -2
	v_add_u32_e32 v1, s19, v156
	v_mov_b32_e32 v2, v0
	v_mov_b32_e32 v3, v0
	v_cmp_gt_u32_e32 vcc, s62, v1
	v_mov_b32_e32 v1, v0
	v_mov_b64_e32 v[70:71], v[2:3]
	s_add_i32 s18, s18, -2
	s_and_b64 s[78:79], s[42:43], vcc
	v_mov_b64_e32 v[68:69], v[0:1]
	s_and_saveexec_b64 s[0:1], s[78:79]
	s_cbranch_execz .LBB0_215
	v_add_u32_e32 v70, s18, v156
	v_mov_b64_e32 v[68:69], s[92:93]
	v_mad_i64_i32 v[68:69], s[78:79], v70, s27, v[68:69]
	v_lshl_add_u64 v[68:69], s[58:59], 1, v[68:69]
	v_mov_b32_e32 v83, v0
	v_lshl_add_u64 v[68:69], v[68:69], 0, v[82:83]
	v_add_co_u32_e32 v68, vcc, 0x2000, v68
	s_nop 1
	v_addc_co_u32_e32 v69, vcc, 0, v69, vcc
	global_load_dwordx4 v[68:71], v[68:69], off offset:1024
